# plus projection GEMM unit order: tiles of the 16 logit columns (long two-wave epilogue) steered to workgroups that own 4 units, via a slot map inside each XCD round
# speedup vs baseline: 1.0490x; 1.0171x over previous
;     __device__ bool next(int i, Unit& u) const {
;     ...
;         const long L = (long)i * G + c; if (L >= nwg) return false;
;         int wgid = (int)L; { const int q = nwg / NXCD, r = nwg % NXCD, xcd = wgid % NXCD, off = wgid / NXCD; wgid = (xcd < r ? xcd * (q + 1) : r * (q + 1) + (xcd - r) * q) + off; }
;         const int nig = WGM * nN, gid = wgid / nig, fm = gid * WGM, gsz = (nM - fm) < WGM ? (nM - fm) : WGM;
;         u.pm = fm + ((wgid % nig) % gsz); u.pn = (wgid % nig) / gsz; return true;
.LBB0_150:
	s_or_b64 exec, exec, s[0:1]
	s_cmpk_lt_i32 s94, 0x495
	s_cselect_b64 s[4:5], -1, 0
	s_waitcnt vmcnt(0)
	v_mov_b32_e32 v21, v0
	s_waitcnt lgkmcnt(0)
	s_barrier
	s_and_b32 s99, s94, 7
	s_mov_b32 s98, 0x1300
	s_mov_b32 s100, 0x88401
	s_mov_b32 s101, 0x3fc01
	s_cmp_eq_u32 s99, 1
	s_cselect_b32 s98, 0x1300, s98
	s_cselect_b32 s100, 0x30401, s100
	s_cselect_b32 s101, 0xe7c01, s101
	s_cmp_eq_u32 s99, 2
	s_cselect_b32 s98, 0x1300, s98
	s_cselect_b32 s100, 0x761, s100
	s_cselect_b32 s101, 0x63f, s101
	s_cmp_eq_u32 s99, 3
	s_cselect_b32 s98, 0x1303, s98
	s_cselect_b32 s100, 0x601, s100
	s_cselect_b32 s101, 0x4df, s101
	s_cmp_eq_u32 s99, 4
	s_cselect_b32 s98, 0x1300, s98
	s_cselect_b32 s100, 0x4a1, s100
	s_cselect_b32 s101, 0x5a1, s101
	s_cmp_eq_u32 s99, 5
	s_cselect_b32 s98, 0x120d, s98
	s_cselect_b32 s100, 0x87dc1, s100
	s_cselect_b32 s101, 0x401, s101
	s_cmp_eq_u32 s99, 6
	s_cselect_b32 s98, 0x1203, s98
	s_cselect_b32 s100, 0xa84e1, s100
	s_cselect_b32 s101, 0x57c01, s101
	s_cmp_eq_u32 s99, 7
	s_cselect_b32 s98, 0x1200, s98
	s_cselect_b32 s100, 0x5ac01, s100
	s_cselect_b32 s101, 0xcac01, s101
	s_movk_i32 s0, 0x400
	v_readfirstlane_b32 s6, v21
	s_mov_b32 s40, 0
	s_movk_i32 s14, 0x400
	s_and_b64 vcc, exec, s[4:5]
	s_cbranch_vccz .LBB0_152
	s_ashr_i32 s1, s94, 31
	s_lshr_b32 s1, s1, 29
	s_add_i32 s1, s94, s1
	s_and_b32 s2, s1, -8
	s_sub_i32 s2, s94, s2
	s_mul_i32 s7, s2, 0x92
	s_add_i32 s7, s7, 5
	s_ashr_i32 s1, s1, 3
	s_mul_i32 s3, s2, 0x93
	s_cmp_lt_i32 s2, 5
	s_cselect_b32 s2, s3, s7
	s_lshr_b32 s99, s1, 5
	s_and_b32 s32, s1, 31
	s_and_b32 s52, s98, 0xff
	s_cmp_eq_u32 s99, 4
	s_cbranch_scc1 .Lp1m_parta
	s_cmp_lt_u32 s99, 2
	s_cselect_b32 s1, s100, s101
	s_and_b32 s54, s99, 1
	s_mul_i32 s54, s54, 10
	s_lshr_b32 s1, s1, s54
	s_and_b32 s54, s1, 31
	s_bfe_u32 s1, s1, 0x50005
	s_mul_i32 s32, s32, s54
	s_add_i32 s32, s32, s1
	s_and_b32 s32, s32, 31
	s_lshl_b32 s99, s99, 5
	s_or_b32 s32, s99, s32
	s_lshr_b32 s99, s98, 8
	s_cmp_lt_u32 s32, s52
	s_cselect_b32 s99, 0, s99
	s_add_i32 s1, s32, s99
	s_branch .Lp1m_donea
.Lp1m_parta:
	s_add_i32 s1, s52, s32
.Lp1m_donea:
	s_add_i32 s2, s2, s1
	s_mul_hi_i32 s1, s2, 0x78787879
	s_lshr_b32 s3, s1, 31
	s_ashr_i32 s1, s1, 5
	s_add_i32 s1, s1, s3
	s_lshl_b32 s7, s1, 2
	s_sub_i32 s3, 0x45, s7
	s_mulk_i32 s1, 0x44
	s_min_u32 s12, s3, 4
	s_sub_i32 s1, s2, s1
	s_sext_i32_i8 s2, s1
	v_cvt_f32_ubyte0_e32 v2, s12
	v_cvt_f32_i32_e32 v1, s2
	v_rcp_iflag_f32_e32 v3, v2
	s_ashr_i32 s2, s2, 30
	s_or_b32 s13, s2, 1
	v_mul_f32_e32 v3, v1, v3
	v_trunc_f32_e32 v3, v3
	v_fma_f32 v1, -v3, v2, v1
	v_cvt_i32_f32_e32 v3, v3
	v_cmp_ge_f32_e64 s[2:3], |v1|, v2
	s_and_b64 s[2:3], s[2:3], exec
	s_cselect_b32 s2, s13, 0
	v_readfirstlane_b32 s3, v3
	s_add_i32 s3, s3, s2
	s_sext_i32_i8 s2, s3
	s_mul_i32 s3, s3, s12
	s_sub_i32 s1, s1, s3
	s_sext_i32_i8 s1, s1
	s_add_i32 s3, s7, s1

;     __device__ bool next(int i, Unit& u) const {
;         u.q = 0;
;         if (samp) { int sidx = c - nwg % G; if (sidx < 0) sidx += G; if (i > 0 || sidx >= 4 * nN) return false; u.pm = 65 + (sidx & 3); u.pn = sidx >> 2; return true; }
;         const long L = (long)i * G + c; if (L >= nwg) return false;
;         int wgid = (int)L; { const int q = nwg / NXCD, r = nwg % NXCD, xcd = wgid % NXCD, off = wgid / NXCD; wgid = (xcd < r ? xcd * (q + 1) : r * (q + 1) + (xcd - r) * q) + off; }
;         const int nig = WGM * nN, gid = wgid / nig, fm = gid * WGM, gsz = (nM - fm) < WGM ? (nM - fm) : WGM;
;         u.pm = fm + ((wgid % nig) % gsz); u.pn = (wgid % nig) / gsz; return true;
;     }
.LBB0_163:
	s_ashr_i32 s6, s26, 3
	s_lshr_b32 s99, s6, 5
	s_and_b32 s32, s6, 31
	s_and_b32 s52, s98, 0xff
	s_cmp_eq_u32 s99, 4
	s_cbranch_scc1 .Lp1m_partb
	s_cmp_lt_u32 s99, 2
	s_cselect_b32 s6, s100, s101
	s_and_b32 s54, s99, 1
	s_mul_i32 s54, s54, 10
	s_lshr_b32 s6, s6, s54
	s_and_b32 s54, s6, 31
	s_bfe_u32 s6, s6, 0x50005
	s_mul_i32 s32, s32, s54
	s_add_i32 s32, s32, s6
	s_and_b32 s32, s32, 31
	s_lshl_b32 s99, s99, 5
	s_or_b32 s32, s99, s32
	s_lshr_b32 s99, s98, 8
	s_cmp_lt_u32 s32, s52
	s_cselect_b32 s99, 0, s99
	s_add_i32 s6, s32, s99
	s_branch .Lp1m_doneb
.Lp1m_partb:
	s_add_i32 s6, s52, s32
.Lp1m_doneb:
	s_add_i32 s6, s38, s6
	s_mul_hi_i32 s7, s6, 0x78787879
	s_lshr_b32 s26, s7, 31
	s_ashr_i32 s7, s7, 5
	s_add_i32 s7, s7, s26
	s_lshl_b32 s26, s7, 2
	s_sub_i32 s27, 0x45, s26
	s_min_i32 s27, s27, 4
	s_abs_i32 s38, s27
	v_cvt_f32_u32_e32 v3, s38
	s_sub_i32 s59, 0, s38
	s_mulk_i32 s7, 0x44
	s_sub_i32 s6, s6, s7
	v_rcp_iflag_f32_e32 v3, v3
	s_abs_i32 s7, s6
	s_xor_b32 s39, s6, s27
	s_ashr_i32 s39, s39, 31
	v_mul_f32_e32 v3, 0x4f7ffffe, v3
	v_cvt_u32_f32_e32 v3, v3
	s_nop 0
	v_readfirstlane_b32 s60, v3
	s_mul_i32 s59, s59, s60
	s_mul_hi_u32 s59, s60, s59
	s_add_i32 s60, s60, s59
	s_mul_hi_u32 s59, s7, s60
	s_mul_i32 s60, s59, s38
	s_sub_i32 s7, s7, s60
	s_add_i32 s61, s59, 1
	s_sub_i32 s60, s7, s38
	s_cmp_ge_u32 s7, s38
	s_cselect_b32 s59, s61, s59
	s_cselect_b32 s7, s60, s7
	s_add_i32 s60, s59, 1
	s_cmp_ge_u32 s7, s38
	s_cselect_b32 s7, s60, s59
	s_xor_b32 s7, s7, s39
	s_sub_i32 s59, s7, s39
	s_mul_i32 s7, s59, s27
	s_sub_i32 s6, s6, s7
	s_add_i32 s60, s26, s6
